# code placement: prompt attention loop shifted by 4 bytes (one s_nop in its preheader, 15 after the loop exit so later code keeps its placement), on top of the prologue over-drain removal
# speedup vs baseline: 1.0115x; 1.0115x over previous
; #define EXPALL(X0, X1) do { _Pragma("unroll") for (int r = 0; r < 16; ++r) { EX2(X0, r); EX2(X1, r); } } while (0)
; #define ROT() do { s_prev = s_cur; s_cur = s_next; s_next = s_nn; s_nn = (s_nn == 3 * P_SLOT) ? 0 : s_nn + P_SLOT; } while (0)
; __device__ __forceinline__ void attn_prompt(Frame& F, int b, int h, int qb, float lam, float mshift) {
;     ...
; #pragma unroll
;     for (int d = 0; d < 4; ++d)
; #pragma unroll
;         for (int r = 0; r < 16; ++r) o[d][r] = 0.f;
; #pragma unroll
;     for (int r = 0; r < 16; ++r) ol[r] = 0.f;
;     f32x16 pA0, pA1, pB0, pB1; bf16x8 pa0, pa1, pa2, pa3; f32x16 CF;
;     ...
;     int s_prev = 0, s_cur = 0, s_next = P_SLOT, s_nn = 2 * P_SLOT;
;     ...
;     asm volatile("s_waitcnt vmcnt(0)" ::: "memory"); __syncthreads();
;     { const float cf = TB[63];
; #pragma unroll
;       for (int r = 0; r < 16; ++r) CF[r] = cf; }
;     { const int j2 = (2 < NT) ? 2 : NT - 1; DMA_TILE(j2, 2 * P_SLOT); }
;     QKT(pA0, pA1, 0, 0); EXPALL(pA0, pA1);
;     ROT();
.LBB0_503:
	v_add_u32_e32 v44, 0, v195
	v_bitop3_b32 v202, v42, v43, 32 bitop3:0x36
	s_waitcnt lgkmcnt(1)
	v_add_u32_e32 v38, v44, v202
	s_waitcnt lgkmcnt(0)
	ds_read_b128 v[34:37], v38
	ds_read_b128 v[38:41], v38 offset:8192
	v_bitop3_b32 v203, v42, v43, 64 bitop3:0x36
	v_add_u32_e32 v45, v44, v203
	s_waitcnt lgkmcnt(1)
	v_mfma_f32_32x32x16_bf16 v[2:17], v[34:37], v[170:173], v[2:17]
	v_bitop3_b32 v204, v42, v43, s84 bitop3:0x36
	v_add_u32_e32 v42, v44, v204
	v_lshlrev_b32_e32 v43, 3, v218
	s_lshr_b32 s83, s3, 6
	s_add_i32 s3, 0, 0x4000
	s_andn2_b64 vcc, exec, s[58:59]
	s_waitcnt lgkmcnt(0)
	v_mfma_f32_32x32x16_bf16 v[18:33], v[38:41], v[170:173], v[18:33]
	ds_read_b128 v[34:37], v45
	ds_read_b128 v[38:41], v45 offset:8192
	s_waitcnt lgkmcnt(0)
	v_mfma_f32_32x32x16_bf16 v[18:33], v[38:41], v[166:169], v[18:33]
	v_lshlrev_b32_e32 v38, 4, v218
	v_and_b32_e32 v44, 0xc0, v38
	ds_read_b128 v[38:41], v42 offset:8192
	v_mfma_f32_32x32x16_bf16 v[2:17], v[34:37], v[166:169], v[2:17]
	ds_read_b128 v[34:37], v42
	s_waitcnt lgkmcnt(0)
	v_mfma_f32_32x32x16_bf16 v[2:17], v[34:37], v[162:165], v[2:17]
	v_lshlrev_b32_e32 v35, 1, v218
	v_and_or_b32 v34, v43, 24, v44
	v_and_b32_e32 v35, 32, v35
	v_and_b32_e32 v36, 0x100, v43
	v_or3_b32 v34, v34, v35, v36
	v_add_u32_e32 v220, s3, v34
	s_nop 5
	v_exp_f32_e32 v146, v2
	v_mfma_f32_32x32x16_bf16 v[18:33], v[38:41], v[162:165], v[18:33]
	v_exp_f32_e32 v147, v3
	v_exp_f32_e32 v148, v4
	v_exp_f32_e32 v149, v5
	v_exp_f32_e32 v150, v6
	v_exp_f32_e32 v151, v7
	v_exp_f32_e32 v152, v8
	v_exp_f32_e32 v153, v9
	s_nop 4
	v_exp_f32_e32 v159, v18
	v_exp_f32_e32 v160, v19
	v_exp_f32_e32 v161, v20
	v_exp_f32_e32 v199, v21
	v_exp_f32_e32 v224, v22
	v_exp_f32_e32 v225, v23
	v_exp_f32_e32 v226, v24
	v_exp_f32_e32 v227, v25
	v_exp_f32_e32 v154, v10
	v_exp_f32_e32 v138, v26
	v_exp_f32_e32 v155, v11
	v_exp_f32_e32 v139, v27
	v_exp_f32_e32 v156, v12
	v_exp_f32_e32 v140, v28
	v_exp_f32_e32 v157, v13
	v_exp_f32_e32 v141, v29
	v_exp_f32_e32 v158, v14
	v_exp_f32_e32 v142, v30
	v_exp_f32_e32 v221, v15
	v_exp_f32_e32 v143, v31
	v_exp_f32_e32 v222, v16
	v_exp_f32_e32 v144, v32
	v_exp_f32_e32 v223, v17
	v_exp_f32_e32 v145, v33
	s_cbranch_vccnz .LBB0_516
	s_add_i32 s10, s76, s14
	v_add_lshl_u32 v2, s10, v217, 2
	v_sub_u32_e32 v2, v194, v2
	v_readlane_b32 s10, v255, 19
	v_mov_b32_e32 v18, 0
	s_add_i32 s84, s83, -2
	s_mov_b32 s66, -1
	s_add_i32 s3, s34, -1
	v_add_u32_e32 v205, s10, v2
	s_mov_b32 s65, 0x18000
	s_mov_b32 s70, 0x10000
	s_mov_b32 s55, 0x8000
	s_mov_b32 s14, 0
	v_mov_b32_e32 v19, v18
	v_mov_b32_e32 v20, v18
	v_mov_b32_e32 v21, v18
	v_mov_b32_e32 v22, v18
	v_mov_b32_e32 v23, v18
	v_mov_b32_e32 v24, v18
	v_mov_b32_e32 v25, v18
	v_mov_b32_e32 v26, v18
	v_mov_b32_e32 v27, v18
	v_mov_b32_e32 v28, v18
	v_mov_b32_e32 v29, v18
	v_mov_b32_e32 v30, v18
	v_mov_b32_e32 v31, v18
	v_mov_b32_e32 v32, v18
	v_mov_b32_e32 v33, v18
	v_mov_b32_e32 v66, v18
	v_mov_b32_e32 v67, v18
	v_mov_b32_e32 v68, v18
	v_mov_b32_e32 v69, v18
	v_mov_b32_e32 v70, v18
	v_mov_b32_e32 v71, v18
	v_mov_b32_e32 v72, v18
	v_mov_b32_e32 v73, v18
	v_mov_b32_e32 v74, v18
	v_mov_b32_e32 v75, v18
	v_mov_b32_e32 v76, v18
	v_mov_b32_e32 v77, v18
	v_mov_b32_e32 v78, v18
	v_mov_b32_e32 v79, v18
	v_mov_b32_e32 v80, v18
	v_mov_b32_e32 v81, v18
	v_mov_b32_e32 v50, v18
	v_mov_b32_e32 v51, v18
	v_mov_b32_e32 v52, v18
	v_mov_b32_e32 v53, v18
	v_mov_b32_e32 v54, v18
	v_mov_b32_e32 v55, v18
	v_mov_b32_e32 v56, v18
	v_mov_b32_e32 v57, v18
	v_mov_b32_e32 v58, v18
	v_mov_b32_e32 v59, v18
	v_mov_b32_e32 v60, v18
	v_mov_b32_e32 v61, v18
	v_mov_b32_e32 v62, v18
	v_mov_b32_e32 v63, v18
	v_mov_b32_e32 v64, v18
	v_mov_b32_e32 v65, v18
	v_mov_b32_e32 v34, v18
	v_mov_b32_e32 v35, v18
	v_mov_b32_e32 v36, v18
	v_mov_b32_e32 v37, v18
	v_mov_b32_e32 v38, v18
	v_mov_b32_e32 v39, v18
	v_mov_b32_e32 v40, v18
	v_mov_b32_e32 v41, v18
	v_mov_b32_e32 v42, v18
	v_mov_b32_e32 v43, v18
	v_mov_b32_e32 v44, v18
	v_mov_b32_e32 v45, v18
	v_mov_b32_e32 v46, v18
	v_mov_b32_e32 v47, v18
	v_mov_b32_e32 v48, v18
	v_mov_b32_e32 v49, v18
	v_mov_b32_e32 v2, v18
	v_mov_b32_e32 v3, v18
	v_mov_b32_e32 v4, v18
	v_mov_b32_e32 v5, v18
	v_mov_b32_e32 v6, v18
	v_mov_b32_e32 v7, v18
	v_mov_b32_e32 v8, v18
	v_mov_b32_e32 v9, v18
	v_mov_b32_e32 v10, v18
	v_mov_b32_e32 v11, v18
	v_mov_b32_e32 v12, v18
	v_mov_b32_e32 v13, v18
	v_mov_b32_e32 v14, v18
	v_mov_b32_e32 v15, v18
	v_mov_b32_e32 v16, v18
	v_mov_b32_e32 v17, v18
	s_nop 0

; #define SBAR() __builtin_amdgcn_sched_barrier(0)
; #define FIN(P0, P1) do { PK4(P0, 0, pa0); PK4(P0, 8, pa1); PK4(P1, 0, pa2); PK4(P1, 8, pa3); } while (0)
; __device__ __forceinline__ void attn_prompt(Frame& F, int b, int h, int qb, float lam, float mshift) {
;     ...
;     for (int j = 1; j + 1 < NT; j += 2) {
;         STEP(pB0, pB1, pA0, pA1, j);
;         STEP(pA0, pA1, pB0, pB1, j + 1);
;     }
;     asm volatile("s_waitcnt vmcnt(0)" ::: "memory");
;     SBAR(); if (vis) { QKT(pB0, pB1, s_cur, NT - 1); } FIN(pA0, pA1); SBAR();
.LBB0_515:
	s_nop 0
	s_nop 0
	s_nop 0
	s_nop 0
	s_nop 0
	s_nop 0
	s_nop 0
	s_nop 0
	s_nop 0
	s_nop 0
	s_nop 0
	s_nop 0
	s_nop 0
	s_nop 0
	s_nop 0
	s_movk_i32 s71, 0xff
	s_movk_i32 s84, 0x60
	s_branch .LBB0_517
